# v31 + static s_setprio 1 for the lagging wave half (4-7) during attention, run 1
# speedup vs baseline: 1.0226x; 1.0090x over previous
; __device__ __forceinline__ float wave_sum(float v) {
; #pragma unroll
;     for (int o = 1; o < 64; o <<= 1) v += __shfl_xor(v, o);
;     return v;
; __global__ void __launch_bounds__(512, 2) fwd_kernel(Args args) {
;     ...
;         const float s1 = wave_sum(lam_q1[lane] * lam_k1[lane]), s2 = wave_sum(lam_q2[lane] * lam_k2[lane]);
;         const float lam = __expf(s1) - __expf(s2) + LAMBDA_INIT;
;         for (int i = 0; ; ++i) { const int L = i * G + vcu, NU = NBATCH * NH * (SEQ / 256); if (L >= NU) break;
;             const int bh = L >> 3, qb = L & 7, Ln = L + G, nbh = Ln >> 3;
;             att::attn_unit(bh >> 3, bh & 7, qb, i == 0, Ln < NU, nbh >> 3, nbh & 7, QO, KB, VB, lam, (char*)lds_raw); }
.LBB0_367:
	s_or_b64 exec, exec, s[0:1]
	v_lshlrev_b32_e32 v1, 2, v162
	s_barrier
	global_load_dword v2, v1, s[48:49]
	global_load_dword v3, v1, s[50:51]
	global_load_dword v4, v1, s[16:17]
	global_load_dword v5, v1, s[18:19]
	v_mbcnt_lo_u32_b32 v1, -1, 0
	v_mbcnt_hi_u32_b32 v6, -1, v1
	v_and_b32_e32 v1, 64, v6
	v_xor_b32_e32 v7, 1, v6
	v_add_u32_e32 v13, 64, v1
	v_cmp_lt_i32_e32 vcc, v7, v13
	v_xor_b32_e32 v8, 2, v6
	v_xor_b32_e32 v9, 4, v6
	v_cndmask_b32_e32 v1, v6, v7, vcc
	v_lshlrev_b32_e32 v1, 2, v1
	v_cmp_lt_i32_e32 vcc, v8, v13
	v_xor_b32_e32 v10, 8, v6
	v_xor_b32_e32 v11, 16, v6
	v_cndmask_b32_e32 v8, v6, v8, vcc
	v_lshlrev_b32_e32 v234, 2, v8
	v_cmp_lt_i32_e32 vcc, v9, v13
	v_xor_b32_e32 v12, 32, v6
	s_cmpk_gt_i32 s86, 0x5ff
	s_mov_b32 s1, 0
	s_waitcnt vmcnt(2)
	v_mul_f32_e32 v7, v2, v3
	ds_bpermute_b32 v7, v1, v7
	s_waitcnt vmcnt(0)
	v_mul_f32_e32 v14, v4, v5
	ds_bpermute_b32 v14, v1, v14
	s_waitcnt lgkmcnt(1)
	v_fmac_f32_e32 v7, v2, v3
	ds_bpermute_b32 v2, v234, v7
	s_waitcnt lgkmcnt(1)
	v_fmac_f32_e32 v14, v4, v5
	ds_bpermute_b32 v3, v234, v14
	v_cndmask_b32_e32 v4, v6, v9, vcc
	v_lshlrev_b32_e32 v235, 2, v4
	s_waitcnt lgkmcnt(1)
	v_add_f32_e32 v2, v7, v2
	ds_bpermute_b32 v4, v235, v2
	s_waitcnt lgkmcnt(1)
	v_add_f32_e32 v3, v14, v3
	ds_bpermute_b32 v5, v235, v3
	v_cmp_lt_i32_e32 vcc, v10, v13
	s_waitcnt lgkmcnt(1)
	v_add_f32_e32 v2, v2, v4
	v_cndmask_b32_e32 v7, v6, v10, vcc
	v_lshlrev_b32_e32 v236, 2, v7
	s_waitcnt lgkmcnt(0)
	v_add_f32_e32 v3, v3, v5
	ds_bpermute_b32 v4, v236, v2
	ds_bpermute_b32 v5, v236, v3
	v_cmp_lt_i32_e32 vcc, v11, v13
	s_waitcnt lgkmcnt(1)
	v_add_f32_e32 v2, v2, v4
	v_cndmask_b32_e32 v7, v6, v11, vcc
	v_lshlrev_b32_e32 v237, 2, v7
	s_waitcnt lgkmcnt(0)
	v_add_f32_e32 v3, v3, v5
	ds_bpermute_b32 v4, v237, v2
	ds_bpermute_b32 v5, v237, v3
	v_cmp_lt_i32_e32 vcc, v12, v13
	s_waitcnt lgkmcnt(1)
	v_add_f32_e32 v2, v2, v4
	v_cndmask_b32_e32 v6, v6, v12, vcc
	v_lshlrev_b32_e32 v6, 2, v6
	s_waitcnt lgkmcnt(0)
	v_add_f32_e32 v3, v3, v5
	ds_bpermute_b32 v4, v6, v2
	ds_bpermute_b32 v5, v6, v3
	s_cbranch_scc1 .LBB0_385
	s_waitcnt lgkmcnt(1)
	v_add_f32_e32 v2, v2, v4
	s_waitcnt lgkmcnt(0)
	v_add_f32_e32 v3, v3, v5
	v_mul_f32_e32 v2, 0x3fb8aa3b, v2
	v_mul_f32_e32 v3, 0x3fb8aa3b, v3
	v_exp_f32_e32 v2, v2
	v_exp_f32_e32 v3, v3
	s_add_u32 s56, s62, 0xd220000
	s_addc_u32 s57, s63, 0
	s_lshl_b32 s72, s86, 8
	s_lshl_b32 s73, s15, 8
	v_writelane_b32 v248, s78, 4
	v_sub_f32_e32 v2, v2, v3
	s_add_u32 s76, s62, 0x13220000
	s_mov_b32 s65, s80
	v_writelane_b32 v248, s79, 5
	v_add_f32_e32 v238, 0x3e4ccccd, v2
	s_addc_u32 s77, s63, 0
	s_movk_i32 s78, 0x1e0
	s_mov_b64 s[2:3], 0x800
	s_mov_b64 s[4:5], 0x20000
	s_mov_b64 s[8:9], 0x20800
	s_mov_b64 s[10:11], 0x3c0000
	s_mov_b64 s[16:17], 0x3c0800
	s_mov_b64 s[18:19], 0x3e0000
	s_mov_b64 s[20:21], 0x3e0800
	v_mov_b32_e32 v203, 0
	s_mov_b64 s[22:23], 0x40000
	s_mov_b64 s[24:25], 0x60000
	s_mov_b64 s[30:31], 0x80000
	s_mov_b64 s[44:45], 0x40800
	v_mov_b32_e32 v239, 0x358637bd
	s_movk_i32 s79, 0xffe0
	s_mov_b32 s0, s86
	s_mov_b32 s80, 0
	v_readfirstlane_b32 s98, v0
	s_lshr_b32 s98, s98, 6
	s_cmp_ge_u32 s98, 4
	s_cselect_b32 s98, 1, 0
	s_cbranch_scc0 .Latt_np
	s_setprio 1
